# sel loop: wave priority by path (two-block steps highest)
# baseline (speedup 1.0000x reference)
.LBB0_1176:
	s_andn2_b64 vcc, exec, s[0:1]
	s_cbranch_vccnz .LBB0_2412
	v_readfirstlane_b32 s0, v0
	s_lshr_b32 s0, s0, 6
	s_cmp_ge_u32 s0, 4
	s_cbranch_scc0 .Lattn_noprio
	s_setprio 0

.Latt1a_entry:
	s_setprio 1
	s_lshr_b32 s6, s9, 2
	s_and_b32 s6, s6, 0x3ffffff8
	s_waitcnt lgkmcnt(0)
	v_add3_u32 v251, s1, v205, v204
	v_add_u32_e32 v16, s6, v209
	s_add_i32 s1, s1, s0
	ds_read_b128 v[50:53], v251
	ds_read_b128 v[54:57], v251 offset:32
	ds_read_b128 v[58:61], v251 offset:64
	ds_read_b128 v[62:65], v251 offset:96
	ds_read_b128 v[66:69], v251 offset:4608
	ds_read_b128 v[70:73], v251 offset:4640
	ds_read_b128 v[74:77], v251 offset:4672
	ds_read_b128 v[78:81], v251 offset:4704
	ds_read_b64 v[16:17], v16
	v_add3_u32 v250, s1, v242, v244
	s_waitcnt lgkmcnt(8)
	v_mfma_f32_32x32x16_bf16 v[146:161], v[50:53], v[114:117], 0
	ds_read_b64_tr_b16 v[212:213], v250 offset:36864
	ds_read_b64_tr_b16 v[214:215], v250 offset:38400
	s_waitcnt lgkmcnt(9)
	v_mfma_f32_32x32x16_bf16 v[146:161], v[54:57], v[118:121], v[146:161]
	ds_read_b64_tr_b16 v[216:217], v250 offset:36928
	ds_read_b64_tr_b16 v[218:219], v250 offset:38464
	s_waitcnt lgkmcnt(10)
	v_mfma_f32_32x32x16_bf16 v[146:161], v[58:61], v[122:125], v[146:161]
	ds_read_b64_tr_b16 v[220:221], v250 offset:39936
	ds_read_b64_tr_b16 v[222:223], v250 offset:41472
	s_waitcnt lgkmcnt(11)
	v_mfma_f32_32x32x16_bf16 v[146:161], v[62:65], v[126:129], v[146:161]
	ds_read_b64_tr_b16 v[224:225], v250 offset:40000
	ds_read_b64_tr_b16 v[226:227], v250 offset:41536
	s_waitcnt lgkmcnt(8)
	v_and_b32_e32 v16, s28, v16
	v_and_b32_e32 v17, s29, v17
	v_cmp_eq_u64_e32 vcc, 0, v[16:17]
	s_nop 2
	v_mfma_f32_32x32x16_bf16 v[162:177], v[66:69], v[114:117], 0
	ds_read_b64_tr_b16 v[228:229], v250 offset:43008
	ds_read_b64_tr_b16 v[230:231], v250 offset:44544
	v_exp_f32_e32 v8, v146
	v_exp_f32_e32 v9, v147
	v_exp_f32_e32 v10, v148
	v_exp_f32_e32 v11, v149
	v_exp_f32_e32 v12, v150
	v_exp_f32_e32 v13, v151
	v_exp_f32_e32 v14, v152
	v_exp_f32_e32 v15, v153
	v_cvt_pk_bf16_f32 v178, v8, v9
	v_cvt_pk_bf16_f32 v179, v10, v11
	v_cvt_pk_bf16_f32 v180, v12, v13
	v_mfma_f32_32x32x16_bf16 v[162:177], v[70:73], v[118:121], v[162:177]
	ds_read_b64_tr_b16 v[232:233], v250 offset:43072
	ds_read_b64_tr_b16 v[234:235], v250 offset:44608
	v_cvt_pk_bf16_f32 v181, v14, v15
	v_add_f32_e32 v8, v8, v9
	v_add_f32_e32 v10, v10, v11
	v_add_f32_e32 v12, v12, v13
	v_add_f32_e32 v14, v14, v15
	v_add_f32_e32 v8, v8, v10
	v_add_f32_e32 v12, v12, v14
	v_add_f32_e32 v202, v8, v12
	v_cndmask_b32_e64 v178, v178, 0, vcc
	v_cndmask_b32_e64 v179, v179, 0, vcc
	v_cndmask_b32_e64 v180, v180, 0, vcc
	v_cndmask_b32_e64 v181, v181, 0, vcc
	v_mfma_f32_32x32x16_bf16 v[162:177], v[74:77], v[122:125], v[162:177]
	ds_read_b64_tr_b16 v[236:237], v250 offset:46080
	ds_read_b64_tr_b16 v[238:239], v250 offset:47616
	v_exp_f32_e32 v8, v154
	v_exp_f32_e32 v9, v155
	v_exp_f32_e32 v10, v156
	v_exp_f32_e32 v11, v157
	v_exp_f32_e32 v12, v158
	v_exp_f32_e32 v13, v159
	v_exp_f32_e32 v14, v160
	v_exp_f32_e32 v15, v161
	v_cvt_pk_bf16_f32 v182, v8, v9
	v_cvt_pk_bf16_f32 v183, v10, v11
	v_cvt_pk_bf16_f32 v184, v12, v13
	v_cvt_pk_bf16_f32 v185, v14, v15
	v_mfma_f32_32x32x16_bf16 v[162:177], v[78:81], v[126:129], v[162:177]
	ds_read_b64_tr_b16 v[4:5], v250 offset:46144
	s_waitcnt lgkmcnt(11)
	ds_read_b64_tr_b16 v[6:7], v250 offset:47680
	s_xor_b32 s0, s23, 1
	s_mul_i32 s1, s0, 0x4800
	s_mulk_i32 s0, 0x6000
	v_add_u32_e32 v207, s1, v206
	s_waitcnt vmcnt(2)
	ds_write_b128 v207, v[134:137]
	ds_write_b128 v207, v[130:133] offset:16
	v_add_f32_e32 v8, v8, v9
	v_add_f32_e32 v10, v10, v11
	v_add_f32_e32 v12, v12, v13
	v_add_f32_e32 v14, v14, v15
	v_add_f32_e32 v8, v8, v10
	v_add_f32_e32 v12, v12, v14
	v_add_f32_e32 v8, v8, v12
	v_add_f32_e32 v202, v202, v8
	v_cndmask_b32_e64 v182, v182, 0, vcc
	v_cndmask_b32_e64 v183, v183, 0, vcc
	v_cndmask_b32_e64 v184, v184, 0, vcc
	v_cndmask_b32_e64 v185, v185, 0, vcc
	v_mfma_f32_32x32x16_bf16 v[18:33], v[212:215], v[178:181], v[18:33]
	v_add_u32_e32 v207, s0, v208
	s_waitcnt vmcnt(0)
	ds_write_b128 v207, v[142:145] offset:36864
	s_waitcnt lgkmcnt(11)
	ds_write_b128 v207, v[138:141] offset:36880
	v_exp_f32_e32 v8, v162
	v_exp_f32_e32 v9, v163
	v_exp_f32_e32 v10, v164
	v_exp_f32_e32 v11, v165
	v_exp_f32_e32 v12, v166
	v_exp_f32_e32 v13, v167
	v_exp_f32_e32 v14, v168
	v_exp_f32_e32 v15, v169
	v_cvt_pk_bf16_f32 v186, v8, v9
	v_cvt_pk_bf16_f32 v187, v10, v11
	v_cvt_pk_bf16_f32 v188, v12, v13
	v_cvt_pk_bf16_f32 v189, v14, v15
	v_mfma_f32_32x32x16_bf16 v[34:49], v[216:219], v[178:181], v[34:49]
	s_waitcnt lgkmcnt(0)
	s_barrier
	v_add_f32_e32 v8, v8, v9
	v_add_f32_e32 v10, v10, v11
	v_add_f32_e32 v12, v12, v13
	v_add_f32_e32 v14, v14, v15
	v_add_f32_e32 v8, v8, v10
	v_add_f32_e32 v12, v12, v14
	v_add_f32_e32 v8, v8, v12
	v_add_f32_e32 v202, v202, v8
	v_cndmask_b32_e64 v186, v186, 0, vcc
	v_cndmask_b32_e64 v187, v187, 0, vcc
	v_cndmask_b32_e64 v188, v188, 0, vcc
	v_cndmask_b32_e64 v189, v189, 0, vcc
	v_mfma_f32_32x32x16_bf16 v[18:33], v[220:223], v[182:185], v[18:33]
	v_exp_f32_e32 v8, v170
	v_exp_f32_e32 v9, v171
	v_exp_f32_e32 v10, v172
	v_exp_f32_e32 v11, v173
	v_exp_f32_e32 v12, v174
	v_exp_f32_e32 v13, v175
	v_exp_f32_e32 v14, v176
	v_exp_f32_e32 v15, v177
	v_cvt_pk_bf16_f32 v190, v8, v9
	v_cvt_pk_bf16_f32 v191, v10, v11
	v_cvt_pk_bf16_f32 v192, v12, v13
	v_cvt_pk_bf16_f32 v193, v14, v15
	v_mfma_f32_32x32x16_bf16 v[34:49], v[224:227], v[182:185], v[34:49]
	v_add_f32_e32 v8, v8, v9
	v_add_f32_e32 v10, v10, v11
	v_add_f32_e32 v12, v12, v13
	v_add_f32_e32 v14, v14, v15
	v_add_f32_e32 v8, v8, v10
	v_add_f32_e32 v12, v12, v14
	v_add_f32_e32 v8, v8, v12
	v_add_f32_e32 v202, v202, v8
	v_cndmask_b32_e64 v190, v190, 0, vcc
	v_cndmask_b32_e64 v191, v191, 0, vcc
	v_cndmask_b32_e64 v192, v192, 0, vcc
	v_cndmask_b32_e64 v193, v193, 0, vcc
	v_mfma_f32_32x32x16_bf16 v[18:33], v[228:231], v[186:189], v[18:33]
	v_cndmask_b32_e64 v202, v202, 0, vcc
	v_add_f32_e32 v252, v2, v202
	v_mov_b32_e32 v2, v252
	v_mfma_f32_32x32x16_bf16 v[34:49], v[232:235], v[186:189], v[34:49]
	v_mov_b32_e32 v16, v252
	s_nop 1
	s_add_i32 s22, s22, 2
	s_add_i32 s9, s9, 1
	v_add_u32_e32 v246, 0x80, v246
	s_cmp_lt_u32 s9, s17
	s_cselect_b64 s[24:25], -1, 0
	s_cbranch_scc0 .Lnx_a1a
	v_min_i32_e32 v240, 0x1fff, v246
	v_ashrrev_i32_e32 v241, 31, v240
	v_lshlrev_b64 v[240:241], 10, v[240:241]
	v_lshl_add_u64 v[240:241], v[210:211], 0, v[240:241]
	global_load_dwordx4 v[130:133], v[240:241], off offset:16
	global_load_dwordx4 v[134:137], v[240:241], off
	global_load_dwordx4 v[138:141], v[240:241], off offset:528
	global_load_dwordx4 v[142:145], v[240:241], off offset:512

.Latt1b_entry:
	s_setprio 1
	s_lshr_b32 s6, s9, 2
	s_and_b32 s6, s6, 0x3ffffff8
	s_waitcnt lgkmcnt(0)
	v_add3_u32 v251, s1, v205, v204
	v_add_u32_e32 v16, s6, v209
	s_add_i32 s1, s1, s0
	ds_read_b128 v[50:53], v251 offset:9216
	ds_read_b128 v[54:57], v251 offset:9248
	ds_read_b128 v[58:61], v251 offset:9280
	ds_read_b128 v[62:65], v251 offset:9312
	ds_read_b128 v[66:69], v251 offset:13824
	ds_read_b128 v[70:73], v251 offset:13856
	ds_read_b128 v[74:77], v251 offset:13888
	ds_read_b128 v[78:81], v251 offset:13920
	ds_read_b64 v[16:17], v16
	v_add3_u32 v250, s1, v242, v244
	s_waitcnt lgkmcnt(8)
	v_mfma_f32_32x32x16_bf16 v[146:161], v[50:53], v[114:117], 0
	ds_read_b64_tr_b16 v[212:213], v250 offset:49152
	ds_read_b64_tr_b16 v[214:215], v250 offset:50688
	s_waitcnt lgkmcnt(9)
	v_mfma_f32_32x32x16_bf16 v[146:161], v[54:57], v[118:121], v[146:161]
	ds_read_b64_tr_b16 v[216:217], v250 offset:49216
	ds_read_b64_tr_b16 v[218:219], v250 offset:50752
	s_waitcnt lgkmcnt(10)
	v_mfma_f32_32x32x16_bf16 v[146:161], v[58:61], v[122:125], v[146:161]
	ds_read_b64_tr_b16 v[220:221], v250 offset:52224
	ds_read_b64_tr_b16 v[222:223], v250 offset:53760
	s_waitcnt lgkmcnt(11)
	v_mfma_f32_32x32x16_bf16 v[146:161], v[62:65], v[126:129], v[146:161]
	ds_read_b64_tr_b16 v[224:225], v250 offset:52288
	ds_read_b64_tr_b16 v[226:227], v250 offset:53824
	s_waitcnt lgkmcnt(8)
	v_and_b32_e32 v16, s26, v16
	v_and_b32_e32 v17, s27, v17
	v_cmp_eq_u64_e32 vcc, 0, v[16:17]
	s_nop 2
	v_mfma_f32_32x32x16_bf16 v[162:177], v[66:69], v[114:117], 0
	ds_read_b64_tr_b16 v[228:229], v250 offset:55296
	ds_read_b64_tr_b16 v[230:231], v250 offset:56832
	v_exp_f32_e32 v8, v146
	v_exp_f32_e32 v9, v147
	v_exp_f32_e32 v10, v148
	v_exp_f32_e32 v11, v149
	v_exp_f32_e32 v12, v150
	v_exp_f32_e32 v13, v151
	v_exp_f32_e32 v14, v152
	v_exp_f32_e32 v15, v153
	v_cvt_pk_bf16_f32 v178, v8, v9
	v_cvt_pk_bf16_f32 v179, v10, v11
	v_cvt_pk_bf16_f32 v180, v12, v13
	v_mfma_f32_32x32x16_bf16 v[162:177], v[70:73], v[118:121], v[162:177]
	ds_read_b64_tr_b16 v[232:233], v250 offset:55360
	ds_read_b64_tr_b16 v[234:235], v250 offset:56896
	v_cvt_pk_bf16_f32 v181, v14, v15
	v_add_f32_e32 v8, v8, v9
	v_add_f32_e32 v10, v10, v11
	v_add_f32_e32 v12, v12, v13
	v_add_f32_e32 v14, v14, v15
	v_add_f32_e32 v8, v8, v10
	v_add_f32_e32 v12, v12, v14
	v_add_f32_e32 v202, v8, v12
	v_cndmask_b32_e64 v178, v178, 0, vcc
	v_cndmask_b32_e64 v179, v179, 0, vcc
	v_cndmask_b32_e64 v180, v180, 0, vcc
	v_cndmask_b32_e64 v181, v181, 0, vcc
	v_mfma_f32_32x32x16_bf16 v[162:177], v[74:77], v[122:125], v[162:177]
	ds_read_b64_tr_b16 v[236:237], v250 offset:58368
	ds_read_b64_tr_b16 v[238:239], v250 offset:59904
	v_exp_f32_e32 v8, v154
	v_exp_f32_e32 v9, v155
	v_exp_f32_e32 v10, v156
	v_exp_f32_e32 v11, v157
	v_exp_f32_e32 v12, v158
	v_exp_f32_e32 v13, v159
	v_exp_f32_e32 v14, v160
	v_exp_f32_e32 v15, v161
	v_cvt_pk_bf16_f32 v182, v8, v9
	v_cvt_pk_bf16_f32 v183, v10, v11
	v_cvt_pk_bf16_f32 v184, v12, v13
	v_cvt_pk_bf16_f32 v185, v14, v15
	v_mfma_f32_32x32x16_bf16 v[162:177], v[78:81], v[126:129], v[162:177]
	ds_read_b64_tr_b16 v[4:5], v250 offset:58432
	s_waitcnt lgkmcnt(11)
	ds_read_b64_tr_b16 v[6:7], v250 offset:59968
	s_xor_b32 s0, s23, 1
	s_mul_i32 s1, s0, 0x4800
	s_mulk_i32 s0, 0x6000
	v_add_u32_e32 v207, s1, v206
	s_waitcnt vmcnt(2)
	ds_write_b128 v207, v[134:137]
	ds_write_b128 v207, v[130:133] offset:16
	v_add_f32_e32 v8, v8, v9
	v_add_f32_e32 v10, v10, v11
	v_add_f32_e32 v12, v12, v13
	v_add_f32_e32 v14, v14, v15
	v_add_f32_e32 v8, v8, v10
	v_add_f32_e32 v12, v12, v14
	v_add_f32_e32 v8, v8, v12
	v_add_f32_e32 v202, v202, v8
	v_cndmask_b32_e64 v182, v182, 0, vcc
	v_cndmask_b32_e64 v183, v183, 0, vcc
	v_cndmask_b32_e64 v184, v184, 0, vcc
	v_cndmask_b32_e64 v185, v185, 0, vcc
	v_mfma_f32_32x32x16_bf16 v[18:33], v[212:215], v[178:181], v[18:33]
	v_add_u32_e32 v207, s0, v208
	s_waitcnt vmcnt(0)
	ds_write_b128 v207, v[142:145] offset:36864
	s_waitcnt lgkmcnt(11)
	ds_write_b128 v207, v[138:141] offset:36880
	v_exp_f32_e32 v8, v162
	v_exp_f32_e32 v9, v163
	v_exp_f32_e32 v10, v164
	v_exp_f32_e32 v11, v165
	v_exp_f32_e32 v12, v166
	v_exp_f32_e32 v13, v167
	v_exp_f32_e32 v14, v168
	v_exp_f32_e32 v15, v169
	v_cvt_pk_bf16_f32 v186, v8, v9
	v_cvt_pk_bf16_f32 v187, v10, v11
	v_cvt_pk_bf16_f32 v188, v12, v13
	v_cvt_pk_bf16_f32 v189, v14, v15
	v_mfma_f32_32x32x16_bf16 v[34:49], v[216:219], v[178:181], v[34:49]
	s_waitcnt lgkmcnt(0)
	s_barrier
	v_add_f32_e32 v8, v8, v9
	v_add_f32_e32 v10, v10, v11
	v_add_f32_e32 v12, v12, v13
	v_add_f32_e32 v14, v14, v15
	v_add_f32_e32 v8, v8, v10
	v_add_f32_e32 v12, v12, v14
	v_add_f32_e32 v8, v8, v12
	v_add_f32_e32 v202, v202, v8
	v_cndmask_b32_e64 v186, v186, 0, vcc
	v_cndmask_b32_e64 v187, v187, 0, vcc
	v_cndmask_b32_e64 v188, v188, 0, vcc
	v_cndmask_b32_e64 v189, v189, 0, vcc
	v_mfma_f32_32x32x16_bf16 v[18:33], v[220:223], v[182:185], v[18:33]
	v_exp_f32_e32 v8, v170
	v_exp_f32_e32 v9, v171
	v_exp_f32_e32 v10, v172
	v_exp_f32_e32 v11, v173
	v_exp_f32_e32 v12, v174
	v_exp_f32_e32 v13, v175
	v_exp_f32_e32 v14, v176
	v_exp_f32_e32 v15, v177
	v_cvt_pk_bf16_f32 v190, v8, v9
	v_cvt_pk_bf16_f32 v191, v10, v11
	v_cvt_pk_bf16_f32 v192, v12, v13
	v_cvt_pk_bf16_f32 v193, v14, v15
	v_mfma_f32_32x32x16_bf16 v[34:49], v[224:227], v[182:185], v[34:49]
	v_add_f32_e32 v8, v8, v9
	v_add_f32_e32 v10, v10, v11
	v_add_f32_e32 v12, v12, v13
	v_add_f32_e32 v14, v14, v15
	v_add_f32_e32 v8, v8, v10
	v_add_f32_e32 v12, v12, v14
	v_add_f32_e32 v8, v8, v12
	v_add_f32_e32 v202, v202, v8
	v_cndmask_b32_e64 v190, v190, 0, vcc
	v_cndmask_b32_e64 v191, v191, 0, vcc
	v_cndmask_b32_e64 v192, v192, 0, vcc
	v_cndmask_b32_e64 v193, v193, 0, vcc
	v_mfma_f32_32x32x16_bf16 v[18:33], v[228:231], v[186:189], v[18:33]
	v_cndmask_b32_e64 v202, v202, 0, vcc
	v_add_f32_e32 v252, v2, v202
	v_mov_b32_e32 v2, v252
	v_mfma_f32_32x32x16_bf16 v[34:49], v[232:235], v[186:189], v[34:49]
	v_mov_b32_e32 v16, v252
	s_nop 1
	s_add_i32 s22, s22, 2
	s_add_i32 s9, s9, 1
	v_add_u32_e32 v246, 0x80, v246
	s_cmp_lt_u32 s9, s17
	s_cselect_b64 s[24:25], -1, 0
	s_cbranch_scc0 .Lnx_a1b
	v_min_i32_e32 v240, 0x1fff, v246
	v_ashrrev_i32_e32 v241, 31, v240
	v_lshlrev_b64 v[240:241], 10, v[240:241]
	v_lshl_add_u64 v[240:241], v[210:211], 0, v[240:241]
	global_load_dwordx4 v[130:133], v[240:241], off offset:16
	global_load_dwordx4 v[134:137], v[240:241], off
	global_load_dwordx4 v[138:141], v[240:241], off offset:528
	global_load_dwordx4 v[142:145], v[240:241], off offset:512

.Lsel_none:
	s_setprio 0
	v_mov_b32_e32 v252, v2
	s_xor_b32 s0, s23, 1
	s_mul_i32 s1, s0, 0x4800
	v_add_u32_e32 v207, s1, v206
	s_mulk_i32 s0, 0x6000
	s_waitcnt vmcnt(2)
	ds_write_b128 v207, v[134:137]
	ds_write_b128 v207, v[130:133] offset:16
	v_add_u32_e32 v207, s0, v208
	s_waitcnt vmcnt(0)
	ds_write_b128 v207, v[142:145] offset:36864
	ds_write_b128 v207, v[138:141] offset:36880
	s_waitcnt lgkmcnt(0)
	s_barrier
	s_branch .Lsel_fast_tail

.Lsel_generic:
	s_setprio 0
	s_lshr_b32 s10, s9, 2
	s_add_i32 s14, s1, 0
	s_and_b32 s10, s10, 0x3ffffff8
	s_add_i32 s15, s14, s0
	s_cmp_gt_u32 s22, s20
	v_add_u32_e32 v197, s10, v209
	s_cselect_b64 s[10:11], -1, 0
	s_cmp_eq_u64 s[6:7], 0
	s_cselect_b64 s[6:7], -1, 0
	s_or_b64 s[6:7], s[10:11], s[6:7]
	v_add_u32_e32 v4, s15, v242
	v_mov_b64_e32 v[80:81], v[48:49]
	v_mov_b64_e32 v[64:65], v[32:33]
	s_and_b64 vcc, exec, s[6:7]
	v_add3_u32 v196, s14, v205, v204
	s_mov_b32 s15, 0x49800000
	v_add_u32_e32 v251, v4, v244
	v_mov_b32_e32 v252, v2
	v_mov_b32_e32 v250, v243
	v_mov_b64_e32 v[78:79], v[46:47]
	v_mov_b64_e32 v[76:77], v[44:45]
	v_mov_b64_e32 v[74:75], v[42:43]
	v_mov_b64_e32 v[72:73], v[40:41]
	v_mov_b64_e32 v[70:71], v[38:39]
	v_mov_b64_e32 v[68:69], v[36:37]
	v_mov_b64_e32 v[66:67], v[34:35]
	v_mov_b64_e32 v[62:63], v[30:31]
	v_mov_b64_e32 v[60:61], v[28:29]
	v_mov_b64_e32 v[58:59], v[26:27]
	v_mov_b64_e32 v[56:57], v[24:25]
	v_mov_b64_e32 v[54:55], v[22:23]
	v_mov_b64_e32 v[52:53], v[20:21]
	v_mov_b64_e32 v[50:51], v[18:19]
	s_cbranch_vccnz .LBB0_1342
	ds_read_b64 v[4:5], v197
	ds_read_b128 v[90:93], v196
	ds_read_b128 v[12:15], v196 offset:32
	ds_read_b128 v[8:11], v196 offset:64
	s_cmp_lg_u32 s20, s22
	s_waitcnt lgkmcnt(3)
	v_and_b32_e32 v17, s29, v5
	v_and_b32_e32 v16, s28, v4
	ds_read_b128 v[94:97], v196 offset:4640
	ds_read_b128 v[82:85], v196 offset:4672
	ds_read_b128 v[98:101], v196 offset:4608
	ds_read_b128 v[86:89], v196 offset:96
	ds_read_b128 v[4:7], v196 offset:4704
	v_cmp_ne_u64_e64 s[6:7], 0, v[16:17]
	s_mov_b64 s[10:11], -1
	v_cmp_neq_f32_e32 vcc, 0, v243
	s_cbranch_scc0 .LBB0_1336
	ds_read_b64_tr_b16 v[150:151], v251 offset:36864
	ds_read_b64_tr_b16 v[152:153], v251 offset:38400
	ds_read_b64_tr_b16 v[112:113], v251 offset:38464
	ds_read_b64_tr_b16 v[110:111], v251 offset:36928
	ds_read_b64_tr_b16 v[106:107], v251 offset:39936
	ds_read_b64_tr_b16 v[108:109], v251 offset:41472
	ds_read_b64_tr_b16 v[104:105], v251 offset:41536
	ds_read_b64_tr_b16 v[102:103], v251 offset:40000
	s_waitcnt lgkmcnt(14)
	v_mfma_f32_32x32x16_bf16 v[66:81], v[90:93], v[114:117], 0
	s_waitcnt lgkmcnt(10)
	v_mfma_f32_32x32x16_bf16 v[50:65], v[98:101], v[114:117], 0
	v_mfma_f32_32x32x16_bf16 v[66:81], v[12:15], v[118:121], v[66:81]
	v_mfma_f32_32x32x16_bf16 v[50:65], v[94:97], v[118:121], v[50:65]
	v_mfma_f32_32x32x16_bf16 v[66:81], v[8:11], v[122:125], v[66:81]
	v_mfma_f32_32x32x16_bf16 v[50:65], v[82:85], v[122:125], v[50:65]
	s_waitcnt lgkmcnt(9)
	v_mfma_f32_32x32x16_bf16 v[66:81], v[86:89], v[126:129], v[66:81]
	s_waitcnt lgkmcnt(8)
	v_mfma_f32_32x32x16_bf16 v[50:65], v[4:7], v[126:129], v[50:65]
	s_mov_b64 vcc, vcc
	s_cbranch_vccz .LBB0_1328
	s_nop 7
	v_sub_f32_e32 v81, v81, v243
	v_sub_f32_e32 v80, v80, v243
	v_sub_f32_e32 v79, v79, v243
	v_sub_f32_e32 v78, v78, v243
	v_sub_f32_e32 v77, v77, v243
	v_sub_f32_e32 v76, v76, v243
	v_sub_f32_e32 v75, v75, v243
	v_sub_f32_e32 v74, v74, v243
	v_sub_f32_e32 v73, v73, v243
	v_sub_f32_e32 v72, v72, v243
	v_sub_f32_e32 v71, v71, v243
	v_sub_f32_e32 v70, v70, v243
	v_sub_f32_e32 v69, v69, v243
	v_sub_f32_e32 v68, v68, v243
	v_sub_f32_e32 v67, v67, v243
	v_sub_f32_e32 v66, v66, v243
	v_sub_f32_e32 v65, v65, v243
	v_sub_f32_e32 v64, v64, v243
	v_sub_f32_e32 v63, v63, v243
	v_sub_f32_e32 v62, v62, v243
	v_sub_f32_e32 v61, v61, v243
	v_sub_f32_e32 v60, v60, v243
	v_sub_f32_e32 v59, v59, v243
	v_sub_f32_e32 v58, v58, v243
	v_sub_f32_e32 v57, v57, v243
	v_sub_f32_e32 v56, v56, v243
	v_sub_f32_e32 v55, v55, v243
	v_sub_f32_e32 v54, v54, v243
	v_sub_f32_e32 v53, v53, v243
	v_sub_f32_e32 v52, v52, v243
	v_sub_f32_e32 v51, v51, v243
	v_sub_f32_e32 v50, v50, v243

.Latt2_entry:
	s_setprio 2
	s_lshr_b32 s6, s9, 2
	s_and_b32 s6, s6, 0x3ffffff8
	s_waitcnt lgkmcnt(0)
	v_add3_u32 v251, s1, v205, v204
	v_add_u32_e32 v16, s6, v209
	s_add_i32 s1, s1, s0
	ds_read_b128 v[50:53], v251
	ds_read_b128 v[54:57], v251 offset:32
	ds_read_b128 v[58:61], v251 offset:64
	ds_read_b128 v[62:65], v251 offset:96
	ds_read_b128 v[66:69], v251 offset:4608
	ds_read_b128 v[70:73], v251 offset:4640
	ds_read_b128 v[74:77], v251 offset:4672
	ds_read_b128 v[78:81], v251 offset:4704
	ds_read_b64 v[16:17], v16
	v_add3_u32 v250, s1, v242, v244
	s_waitcnt lgkmcnt(8)
	v_mfma_f32_32x32x16_bf16 v[146:161], v[50:53], v[114:117], 0
	ds_read_b128 v[82:85], v251 offset:9216
	ds_read_b128 v[86:89], v251 offset:9248
	s_waitcnt lgkmcnt(9)
	v_mfma_f32_32x32x16_bf16 v[146:161], v[54:57], v[118:121], v[146:161]
	ds_read_b128 v[90:93], v251 offset:9280
	ds_read_b128 v[94:97], v251 offset:9312
	s_waitcnt lgkmcnt(10)
	v_mfma_f32_32x32x16_bf16 v[146:161], v[58:61], v[122:125], v[146:161]
	ds_read_b128 v[98:101], v251 offset:13824
	ds_read_b128 v[102:105], v251 offset:13856
	s_waitcnt lgkmcnt(11)
	v_mfma_f32_32x32x16_bf16 v[146:161], v[62:65], v[126:129], v[146:161]
	ds_read_b128 v[106:109], v251 offset:13888
	ds_read_b128 v[110:113], v251 offset:13920
	s_waitcnt lgkmcnt(8)
	v_and_b32_e32 v240, s28, v16
	v_and_b32_e32 v241, s29, v17
	v_and_b32_e32 v16, s26, v16
	v_and_b32_e32 v17, s27, v17
	v_cmp_eq_u64_e32 vcc, 0, v[240:241]
	v_cmp_eq_u64_e64 s[6:7], 0, v[16:17]
	v_mfma_f32_32x32x16_bf16 v[162:177], v[66:69], v[114:117], 0
	ds_read_b64_tr_b16 v[212:213], v250 offset:36864
	ds_read_b64_tr_b16 v[214:215], v250 offset:38400
	v_exp_f32_e32 v8, v146
	v_exp_f32_e32 v9, v147
	v_exp_f32_e32 v10, v148
	v_exp_f32_e32 v11, v149
	v_exp_f32_e32 v12, v150
	v_exp_f32_e32 v13, v151
	v_exp_f32_e32 v14, v152
	v_mfma_f32_32x32x16_bf16 v[162:177], v[70:73], v[118:121], v[162:177]
	ds_read_b64_tr_b16 v[216:217], v250 offset:36928
	ds_read_b64_tr_b16 v[218:219], v250 offset:38464
	v_exp_f32_e32 v15, v153
	v_cvt_pk_bf16_f32 v178, v8, v9
	v_cvt_pk_bf16_f32 v179, v10, v11
	v_cvt_pk_bf16_f32 v180, v12, v13
	v_cvt_pk_bf16_f32 v181, v14, v15
	v_add_f32_e32 v8, v8, v9
	v_add_f32_e32 v10, v10, v11
	v_add_f32_e32 v12, v12, v13
	v_mfma_f32_32x32x16_bf16 v[162:177], v[74:77], v[122:125], v[162:177]
	ds_read_b64_tr_b16 v[220:221], v250 offset:39936
	ds_read_b64_tr_b16 v[222:223], v250 offset:41472
	v_add_f32_e32 v14, v14, v15
	v_add_f32_e32 v8, v8, v10
	v_add_f32_e32 v12, v12, v14
	v_add_f32_e32 v202, v8, v12
	v_cndmask_b32_e64 v178, v178, 0, vcc
	v_cndmask_b32_e64 v179, v179, 0, vcc
	v_cndmask_b32_e64 v180, v180, 0, vcc
	v_cndmask_b32_e64 v181, v181, 0, vcc
	v_mfma_f32_32x32x16_bf16 v[162:177], v[78:81], v[126:129], v[162:177]
	ds_read_b64_tr_b16 v[224:225], v250 offset:40000
	s_waitcnt lgkmcnt(11)
	ds_read_b64_tr_b16 v[226:227], v250 offset:41536
	v_exp_f32_e32 v8, v154
	v_exp_f32_e32 v9, v155
	v_exp_f32_e32 v10, v156
	v_exp_f32_e32 v11, v157
	v_exp_f32_e32 v12, v158
	v_exp_f32_e32 v13, v159
	v_exp_f32_e32 v14, v160
	v_exp_f32_e32 v15, v161
	v_mfma_f32_32x32x16_bf16 v[50:65], v[82:85], v[114:117], 0
	ds_read_b64_tr_b16 v[228:229], v250 offset:43008
	ds_read_b64_tr_b16 v[230:231], v250 offset:44544
	v_cvt_pk_bf16_f32 v182, v8, v9
	v_cvt_pk_bf16_f32 v183, v10, v11
	v_cvt_pk_bf16_f32 v184, v12, v13
	v_cvt_pk_bf16_f32 v185, v14, v15
	v_add_f32_e32 v8, v8, v9
	v_add_f32_e32 v10, v10, v11
	v_add_f32_e32 v12, v12, v13
	v_add_f32_e32 v14, v14, v15
	v_mfma_f32_32x32x16_bf16 v[50:65], v[86:89], v[118:121], v[50:65]
	ds_read_b64_tr_b16 v[232:233], v250 offset:43072
	s_waitcnt lgkmcnt(11)
	ds_read_b64_tr_b16 v[234:235], v250 offset:44608
	v_add_f32_e32 v8, v8, v10
	v_add_f32_e32 v12, v12, v14
	v_add_f32_e32 v8, v8, v12
	v_add_f32_e32 v202, v202, v8
	v_cndmask_b32_e64 v182, v182, 0, vcc
	v_cndmask_b32_e64 v183, v183, 0, vcc
	v_cndmask_b32_e64 v184, v184, 0, vcc
	v_cndmask_b32_e64 v185, v185, 0, vcc
	v_mfma_f32_32x32x16_bf16 v[50:65], v[90:93], v[122:125], v[50:65]
	ds_read_b64_tr_b16 v[236:237], v250 offset:46080
	ds_read_b64_tr_b16 v[238:239], v250 offset:47616
	ds_read_b64_tr_b16 v[146:147], v250 offset:49152
	s_waitcnt lgkmcnt(11)
	ds_read_b64_tr_b16 v[148:149], v250 offset:50688
	v_exp_f32_e32 v8, v162
	v_exp_f32_e32 v9, v163
	v_exp_f32_e32 v10, v164
	v_exp_f32_e32 v11, v165
	v_exp_f32_e32 v12, v166
	v_exp_f32_e32 v13, v167
	v_exp_f32_e32 v14, v168
	v_exp_f32_e32 v15, v169
	v_mfma_f32_32x32x16_bf16 v[50:65], v[94:97], v[126:129], v[50:65]
	ds_read_b64_tr_b16 v[4:5], v250 offset:46144
	ds_read_b64_tr_b16 v[6:7], v250 offset:47680
	ds_read_b64_tr_b16 v[150:151], v250 offset:49216
	s_waitcnt lgkmcnt(11)
	ds_read_b64_tr_b16 v[152:153], v250 offset:50752
	v_cvt_pk_bf16_f32 v186, v8, v9
	v_cvt_pk_bf16_f32 v187, v10, v11
	v_cvt_pk_bf16_f32 v188, v12, v13
	v_cvt_pk_bf16_f32 v189, v14, v15
	v_add_f32_e32 v8, v8, v9
	v_add_f32_e32 v10, v10, v11
	v_add_f32_e32 v12, v12, v13
	v_add_f32_e32 v14, v14, v15
	v_mfma_f32_32x32x16_bf16 v[66:81], v[98:101], v[114:117], 0
	ds_read_b64_tr_b16 v[154:155], v250 offset:52224
	ds_read_b64_tr_b16 v[156:157], v250 offset:53760
	ds_read_b64_tr_b16 v[82:83], v250 offset:55296
	s_waitcnt lgkmcnt(11)
	ds_read_b64_tr_b16 v[84:85], v250 offset:56832
	v_add_f32_e32 v8, v8, v10
	v_add_f32_e32 v12, v12, v14
	v_add_f32_e32 v8, v8, v12
	v_add_f32_e32 v202, v202, v8
	v_cndmask_b32_e64 v186, v186, 0, vcc
	v_cndmask_b32_e64 v187, v187, 0, vcc
	v_cndmask_b32_e64 v188, v188, 0, vcc
	v_cndmask_b32_e64 v189, v189, 0, vcc
	v_mfma_f32_32x32x16_bf16 v[66:81], v[102:105], v[118:121], v[66:81]
	ds_read_b64_tr_b16 v[158:159], v250 offset:52288
	ds_read_b64_tr_b16 v[160:161], v250 offset:53824
	ds_read_b64_tr_b16 v[86:87], v250 offset:55360
	s_waitcnt lgkmcnt(11)
	ds_read_b64_tr_b16 v[88:89], v250 offset:56896
	v_exp_f32_e32 v8, v170
	v_exp_f32_e32 v9, v171
	v_exp_f32_e32 v10, v172
	v_exp_f32_e32 v11, v173
	v_exp_f32_e32 v12, v174
	v_exp_f32_e32 v13, v175
	v_exp_f32_e32 v14, v176
	v_exp_f32_e32 v15, v177
	v_mfma_f32_32x32x16_bf16 v[66:81], v[106:109], v[122:125], v[66:81]
	ds_read_b64_tr_b16 v[90:91], v250 offset:58368
	ds_read_b64_tr_b16 v[92:93], v250 offset:59904
	s_xor_b32 s0, s23, 1
	s_mul_i32 s1, s0, 0x4800
	s_mulk_i32 s0, 0x6000
	v_add_u32_e32 v207, s1, v206
	s_waitcnt vmcnt(2)
	ds_write_b128 v207, v[134:137]
	s_waitcnt lgkmcnt(11)
	ds_write_b128 v207, v[130:133] offset:16
	v_cvt_pk_bf16_f32 v190, v8, v9
	v_cvt_pk_bf16_f32 v191, v10, v11
	v_cvt_pk_bf16_f32 v192, v12, v13
	v_cvt_pk_bf16_f32 v193, v14, v15
	v_add_f32_e32 v8, v8, v9
	v_add_f32_e32 v10, v10, v11
	v_add_f32_e32 v12, v12, v13
	v_add_f32_e32 v14, v14, v15
	v_mfma_f32_32x32x16_bf16 v[66:81], v[110:113], v[126:129], v[66:81]
	ds_read_b64_tr_b16 v[94:95], v250 offset:58432
	ds_read_b64_tr_b16 v[96:97], v250 offset:59968
	v_add_u32_e32 v207, s0, v208
	s_waitcnt vmcnt(0)
	ds_write_b128 v207, v[142:145] offset:36864
	s_waitcnt lgkmcnt(11)
	ds_write_b128 v207, v[138:141] offset:36880
	v_add_f32_e32 v8, v8, v10
	v_add_f32_e32 v12, v12, v14
	v_add_f32_e32 v8, v8, v12
	v_add_f32_e32 v202, v202, v8
	v_cndmask_b32_e64 v190, v190, 0, vcc
	v_cndmask_b32_e64 v191, v191, 0, vcc
	v_cndmask_b32_e64 v192, v192, 0, vcc
	v_cndmask_b32_e64 v193, v193, 0, vcc
	v_mfma_f32_32x32x16_bf16 v[18:33], v[212:215], v[178:181], v[18:33]
	s_waitcnt lgkmcnt(0)
	s_barrier
	v_exp_f32_e32 v8, v50
	v_exp_f32_e32 v9, v51
	v_exp_f32_e32 v10, v52
	v_exp_f32_e32 v11, v53
	v_exp_f32_e32 v12, v54
	v_exp_f32_e32 v13, v55
	v_exp_f32_e32 v14, v56
	v_exp_f32_e32 v15, v57
	v_mfma_f32_32x32x16_bf16 v[34:49], v[216:219], v[178:181], v[34:49]
	v_cvt_pk_bf16_f32 v178, v8, v9
	v_cvt_pk_bf16_f32 v179, v10, v11
	v_cvt_pk_bf16_f32 v180, v12, v13
	v_cvt_pk_bf16_f32 v181, v14, v15
	v_add_f32_e32 v8, v8, v9
	v_add_f32_e32 v10, v10, v11
	v_add_f32_e32 v12, v12, v13
	v_add_f32_e32 v14, v14, v15
	v_mfma_f32_32x32x16_bf16 v[18:33], v[220:223], v[182:185], v[18:33]
	v_add_f32_e32 v8, v8, v10
	v_add_f32_e32 v12, v12, v14
	v_add_f32_e32 v203, v8, v12
	v_cndmask_b32_e64 v178, v178, 0, s[6:7]
	v_cndmask_b32_e64 v179, v179, 0, s[6:7]
	v_cndmask_b32_e64 v180, v180, 0, s[6:7]
	v_cndmask_b32_e64 v181, v181, 0, s[6:7]
	v_exp_f32_e32 v8, v58
	v_mfma_f32_32x32x16_bf16 v[34:49], v[224:227], v[182:185], v[34:49]
	v_exp_f32_e32 v9, v59
	v_exp_f32_e32 v10, v60
	v_exp_f32_e32 v11, v61
	v_exp_f32_e32 v12, v62
	v_exp_f32_e32 v13, v63
	v_exp_f32_e32 v14, v64
	v_exp_f32_e32 v15, v65
	v_cvt_pk_bf16_f32 v182, v8, v9
	v_mfma_f32_32x32x16_bf16 v[18:33], v[228:231], v[186:189], v[18:33]
	v_cvt_pk_bf16_f32 v183, v10, v11
	v_cvt_pk_bf16_f32 v184, v12, v13
	v_cvt_pk_bf16_f32 v185, v14, v15
	v_add_f32_e32 v8, v8, v9
	v_add_f32_e32 v10, v10, v11
	v_add_f32_e32 v12, v12, v13
	v_add_f32_e32 v14, v14, v15
	v_add_f32_e32 v8, v8, v10
	v_mfma_f32_32x32x16_bf16 v[34:49], v[232:235], v[186:189], v[34:49]
	v_add_f32_e32 v12, v12, v14
	v_add_f32_e32 v8, v8, v12
	v_add_f32_e32 v203, v203, v8
	v_cndmask_b32_e64 v182, v182, 0, s[6:7]
	v_cndmask_b32_e64 v183, v183, 0, s[6:7]
	v_cndmask_b32_e64 v184, v184, 0, s[6:7]
	v_cndmask_b32_e64 v185, v185, 0, s[6:7]
	v_exp_f32_e32 v8, v66
	v_mfma_f32_32x32x16_bf16 v[18:33], v[236:239], v[190:193], v[18:33]
	v_exp_f32_e32 v9, v67
	v_exp_f32_e32 v10, v68
	v_exp_f32_e32 v11, v69
	v_exp_f32_e32 v12, v70
	v_exp_f32_e32 v13, v71
	v_exp_f32_e32 v14, v72
	v_exp_f32_e32 v15, v73
	v_cvt_pk_bf16_f32 v186, v8, v9
	v_mfma_f32_32x32x16_bf16 v[34:49], v[4:7], v[190:193], v[34:49]
	v_cvt_pk_bf16_f32 v187, v10, v11
	v_cvt_pk_bf16_f32 v188, v12, v13
	v_cvt_pk_bf16_f32 v189, v14, v15
	v_add_f32_e32 v8, v8, v9
	v_add_f32_e32 v10, v10, v11
	v_add_f32_e32 v12, v12, v13
	v_add_f32_e32 v14, v14, v15
	v_add_f32_e32 v8, v8, v10
	v_mfma_f32_32x32x16_bf16 v[18:33], v[146:149], v[178:181], v[18:33]
	v_add_f32_e32 v12, v12, v14
	v_add_f32_e32 v8, v8, v12
	v_add_f32_e32 v203, v203, v8
	v_cndmask_b32_e64 v186, v186, 0, s[6:7]
	v_cndmask_b32_e64 v187, v187, 0, s[6:7]
	v_cndmask_b32_e64 v188, v188, 0, s[6:7]
	v_cndmask_b32_e64 v189, v189, 0, s[6:7]
	v_exp_f32_e32 v8, v74
	v_mfma_f32_32x32x16_bf16 v[34:49], v[150:153], v[178:181], v[34:49]
	v_exp_f32_e32 v9, v75
	v_exp_f32_e32 v10, v76
	v_exp_f32_e32 v11, v77
	v_exp_f32_e32 v12, v78
	v_exp_f32_e32 v13, v79
	v_exp_f32_e32 v14, v80
	v_exp_f32_e32 v15, v81
	v_cvt_pk_bf16_f32 v190, v8, v9
	v_mfma_f32_32x32x16_bf16 v[18:33], v[154:157], v[182:185], v[18:33]
	v_cvt_pk_bf16_f32 v191, v10, v11
	v_cvt_pk_bf16_f32 v192, v12, v13
	v_cvt_pk_bf16_f32 v193, v14, v15
	v_add_f32_e32 v8, v8, v9
	v_add_f32_e32 v10, v10, v11
	v_add_f32_e32 v12, v12, v13
	v_add_f32_e32 v14, v14, v15
	v_add_f32_e32 v8, v8, v10
	v_mfma_f32_32x32x16_bf16 v[34:49], v[158:161], v[182:185], v[34:49]
	v_add_f32_e32 v12, v12, v14
	v_add_f32_e32 v8, v8, v12
	v_add_f32_e32 v203, v203, v8
	v_cndmask_b32_e64 v190, v190, 0, s[6:7]
	v_cndmask_b32_e64 v191, v191, 0, s[6:7]
	v_cndmask_b32_e64 v192, v192, 0, s[6:7]
	v_cndmask_b32_e64 v193, v193, 0, s[6:7]
	v_cndmask_b32_e64 v202, v202, 0, vcc
	v_mfma_f32_32x32x16_bf16 v[18:33], v[82:85], v[186:189], v[18:33]
	v_cndmask_b32_e64 v203, v203, 0, s[6:7]
	v_add_f32_e32 v202, v202, v203
	v_add_f32_e32 v252, v2, v202
	v_mov_b32_e32 v2, v252
	s_add_i32 s22, s22, 2
	s_add_i32 s9, s9, 1
	v_add_u32_e32 v246, 0x80, v246
	s_cmp_lt_u32 s9, s17
	s_cselect_b64 s[24:25], -1, 0
	s_cbranch_scc0 .Lnx_a2
	v_min_i32_e32 v240, 0x1fff, v246
	v_ashrrev_i32_e32 v241, 31, v240
	v_lshlrev_b64 v[240:241], 10, v[240:241]
	v_lshl_add_u64 v[240:241], v[210:211], 0, v[240:241]
	global_load_dwordx4 v[130:133], v[240:241], off offset:16
	global_load_dwordx4 v[134:137], v[240:241], off
	global_load_dwordx4 v[138:141], v[240:241], off offset:528
	global_load_dwordx4 v[142:145], v[240:241], off offset:512

.Lsel_exit:
	s_setprio 0
	v_mov_b32_e32 v2, v252
	s_nop 1
	v_permlane32_swap_b32_e32 v252, v2
	v_mov_b32_e32 v5, v0
	v_add_f32_e32 v4, v252, v2
	v_mov_b32_e32 v2, 0
	v_readfirstlane_b32 s0, v5
	v_cmp_lt_f32_e32 vcc, 0, v4
	s_and_saveexec_b64 s[2:3], vcc
	v_readlane_b32 s48, v255, 60
	v_readlane_b32 s49, v255, 61
	v_readlane_b32 s23, v255, 41
	s_cbranch_execz .LBB0_1363
	s_add_i32 s1, s12, s21
	s_ashr_i32 s0, s0, 3
	v_lshrrev_b32_e32 v2, 2, v5
	s_and_b32 s0, s0, -8
	v_and_or_b32 v2, v2, 7, s1
	v_add_u32_e32 v2, s0, v2
	v_mov_b64_e32 v[6:7], s[48:49]
	s_movk_i32 s0, 0xc0
	v_mad_i64_i32 v[6:7], s[0:1], v2, s0, v[6:7]
	v_and_or_b32 v2, v5, 3, s23
	v_mul_u32_u24_e32 v2, 3, v2
	v_lshlrev_b32_e32 v2, 2, v2
	v_lshl_add_u64 v[6:7], v[6:7], 0, v[2:3]
	global_load_dword v2, v[6:7], off offset:4
	s_waitcnt vmcnt(0)
	v_div_scale_f32 v5, s[0:1], v4, v4, v2
	v_rcp_f32_e32 v6, v5
	v_div_scale_f32 v7, vcc, v2, v4, v2
	v_fma_f32 v8, -v5, v6, 1.0
	v_fmac_f32_e32 v6, v8, v6
	v_mul_f32_e32 v8, v7, v6
	v_fma_f32 v9, -v5, v8, v7
	v_fmac_f32_e32 v8, v9, v6
	v_fma_f32 v5, -v5, v8, v7
	v_div_fmas_f32 v5, v5, v6, v8
	v_div_fixup_f32 v2, v5, v4, v2
